# v22 + next K/V tile global loads issued at the top of the attention tile loop instead of just before P.V
# speedup vs baseline: 1.0065x; 1.0033x over previous
.LBB0_796:
	s_cmp_ge_u32 s53, s26
	s_cbranch_scc1 .Lkv_skip
	s_add_i32 s7, s69, s23
	s_add_i32 s7, s7, 1
	s_lshl_b32 s7, s7, 6
	s_add_i32 s7, s7, s28
	s_add_i32 s14, s60, s68
	s_cmp_lt_u32 s53, s25
	s_cselect_b64 s[12:13], -1, 0
	s_cselect_b32 s14, s7, s14
	s_cselect_b32 s16, s29, s35
	v_mbcnt_lo_u32_b32 v224, -1, 0
	v_mbcnt_hi_u32_b32 v224, -1, v224
	v_add_u32_e32 v228, s1, v224
	v_ashrrev_i32_e32 v228, 4, v228
	v_add_u32_e32 v225, s14, v228
	v_med3_i32 v228, v225, 0, v237
	v_cndmask_b32_e64 v228, v225, v228, s[12:13]
	v_add_u32_e32 v228, s16, v228
	v_ashrrev_i32_e32 v229, 31, v228
	v_lshlrev_b32_e32 v224, 4, v224
	v_lshlrev_b64 v[228:229], 9, v[228:229]
	v_and_b32_e32 v224, 0xf0, v224
	v_or_b32_e32 v228, v228, v224
	v_lshl_add_u64 v[230:231], s[46:47], 0, v[228:229]
	v_lshl_add_u64 v[228:229], s[48:49], 0, v[228:229]
	global_load_dwordx4 v[130:133], v[230:231], off
	global_load_dwordx4 v[134:137], v[230:231], off offset:256
	global_load_dwordx4 v[138:141], v[228:229], off
	global_load_dwordx4 v[142:145], v[228:229], off offset:256
	v_add_u32_e32 v228, 32, v225
	v_med3_i32 v229, v228, 0, v237
	v_cndmask_b32_e64 v228, v228, v229, s[12:13]
	v_add_u32_e32 v228, s16, v228
	v_ashrrev_i32_e32 v229, 31, v228
	v_lshlrev_b64 v[228:229], 9, v[228:229]
	v_or_b32_e32 v228, v228, v224
	v_lshl_add_u64 v[230:231], s[46:47], 0, v[228:229]
	v_lshl_add_u64 v[228:229], s[48:49], 0, v[228:229]
	global_load_dwordx4 v[146:149], v[230:231], off
	global_load_dwordx4 v[150:153], v[230:231], off offset:256
	global_load_dwordx4 v[154:157], v[228:229], off
	global_load_dwordx4 v[158:161], v[228:229], off offset:256

; __device__ __forceinline__ int v_rd_base(int lane) { return ((lane & 3) << 3) | (((lane >> 2) & 3) << 6) | (((lane >> 4) & 1) << 5) | (((lane >> 5) & 1) << 8); }
; template <int OFF> __device__ __forceinline__ s16x4 tr_read(int vb) { s16x4 r; asm volatile("ds_read_b64_tr_b16 %0, %1 offset:%2" : "=&v"(r) : "v"(vb), "i"(OFF) : "memory"); return r; }
; template <int D0> __device__ __forceinline__ void pv_one4(f32x16& od, int vb, bf16x8 pa0, bf16x8 pa1, bf16x8 pa2, bf16x8 pa3) {
;     const s16x4 l0 = tr_read<v_rd_off(D0, 0, 0)>(vb), h0 = tr_read<v_rd_off(D0, 0, 1)>(vb), l1 = tr_read<v_rd_off(D0, 1, 0)>(vb), h1 = tr_read<v_rd_off(D0, 1, 1)>(vb);
;     const s16x4 l2 = tr_read<v_rd_off(D0, 2, 0)>(vb), h2 = tr_read<v_rd_off(D0, 2, 1)>(vb), l3 = tr_read<v_rd_off(D0, 3, 0)>(vb), h3 = tr_read<v_rd_off(D0, 3, 1)>(vb);
;     asm volatile("s_waitcnt lgkmcnt(0)" ::: "memory"); __builtin_amdgcn_sched_barrier(0);
;     ...
;     od = __builtin_amdgcn_mfma_f32_32x32x16_bf16(pa0, AT_PK(l0, h0), od, 0, 0, 0);
;     od = __builtin_amdgcn_mfma_f32_32x32x16_bf16(pa1, AT_PK(l1, h1), od, 0, 0, 0);
;     od = __builtin_amdgcn_mfma_f32_32x32x16_bf16(pa2, AT_PK(l2, h2), od, 0, 0, 0);
;     od = __builtin_amdgcn_mfma_f32_32x32x16_bf16(pa3, AT_PK(l3, h3), od, 0, 0, 0);
;     ...
; }
; __device__ __forceinline__ void attn_mfma(LAS unsigned char* lds, int layer, int G, const int wave_s) {
;     ...
;             AT_PK4(p0, 0, pa0); AT_PK4(p0, 8, pa1); AT_PK4(p1, 0, pa2); AT_PK4(p1, 8, pa3);
;     ...
;             if (i + 1 < NT) AT_SLOAD(i + 1);
;             { const int vb = (int)(lbase + bf * AT_BUF + 32768 + kv * 16384) + v_rd_base(lane);
;               pv_one4<0>(o[0], vb, pa0, pa1, pa2, pa3); pv_one4<1>(o[1], vb, pa0, pa1, pa2, pa3); pv_one4<2>(o[2], vb, pa0, pa1, pa2, pa3); pv_one4<3>(o[3], vb, pa0, pa1, pa2, pa3); }
;             if (i + 1 < NT) AT_SWRITE(bf ^ 1);
.LBB0_802:
	s_add_i32 s69, s69, 1
	v_cvt_pk_bf16_f32 v66, v66, v67
	v_cvt_pk_bf16_f32 v67, v68, v69
	v_cvt_pk_bf16_f32 v68, v70, v71
	v_cvt_pk_bf16_f32 v69, v72, v73
	v_cvt_pk_bf16_f32 v70, v74, v75
	v_cvt_pk_bf16_f32 v71, v76, v77
	v_cvt_pk_bf16_f32 v72, v78, v79
	v_cvt_pk_bf16_f32 v73, v80, v239
	v_cvt_pk_bf16_f32 v74, v218, v219
	v_cvt_pk_bf16_f32 v75, v217, v85
	v_cvt_pk_bf16_f32 v76, v86, v87
	v_cvt_pk_bf16_f32 v77, v88, v89
	v_cvt_pk_bf16_f32 v78, v90, v91
	v_cvt_pk_bf16_f32 v79, v92, v93
	v_cvt_pk_bf16_f32 v80, v94, v95
	v_cvt_pk_bf16_f32 v81, v96, v81
	s_cmp_lt_u32 s53, s26
	v_permlane32_swap_b32_e32 v66, v68
	v_permlane32_swap_b32_e32 v67, v69
	v_permlane32_swap_b32_e32 v70, v72
	v_permlane32_swap_b32_e32 v71, v73
	v_permlane32_swap_b32_e32 v74, v76
	v_permlane32_swap_b32_e32 v75, v77
	v_permlane32_swap_b32_e32 v78, v80
	s_cselect_b64 s[54:55], -1, 0
	s_cmp_ge_u32 s53, s26
	v_permlane32_swap_b32_e32 v79, v81
	s_cbranch_scc1 .LBB0_808
.LBB0_808:
	v_add_u32_e32 v85, s71, v191
	ds_read_b64_tr_b16 v[86:87], v85 offset:0
	ds_read_b64_tr_b16 v[88:89], v85 offset:0x800
	ds_read_b64_tr_b16 v[90:91], v85 offset:0x1000
	ds_read_b64_tr_b16 v[92:93], v85 offset:0x1800
	ds_read_b64_tr_b16 v[94:95], v85 offset:0x2000
	ds_read_b64_tr_b16 v[96:97], v85 offset:0x2800
	ds_read_b64_tr_b16 v[218:219], v85 offset:0x3000
	ds_read_b64_tr_b16 v[220:221], v85 offset:0x3800
	s_waitcnt lgkmcnt(0)
	s_nop 0
	v_mfma_f32_32x32x16_bf16 v[50:65], v[66:69], v[86:89], v[50:65]
	ds_read_b64_tr_b16 v[86:87], v85 offset:0x200
	ds_read_b64_tr_b16 v[88:89], v85 offset:0xa00
	v_mfma_f32_32x32x16_bf16 v[50:65], v[70:73], v[90:93], v[50:65]
	ds_read_b64_tr_b16 v[90:91], v85 offset:0x1200
	ds_read_b64_tr_b16 v[92:93], v85 offset:0x1a00
	v_mfma_f32_32x32x16_bf16 v[50:65], v[74:77], v[94:97], v[50:65]
	ds_read_b64_tr_b16 v[94:95], v85 offset:0x2200
	ds_read_b64_tr_b16 v[96:97], v85 offset:0x2a00
	v_mfma_f32_32x32x16_bf16 v[50:65], v[78:81], v[218:221], v[50:65]
	ds_read_b64_tr_b16 v[218:219], v85 offset:0x3200
	ds_read_b64_tr_b16 v[220:221], v85 offset:0x3a00
	s_waitcnt lgkmcnt(0)
	v_mfma_f32_32x32x16_bf16 v[34:49], v[66:69], v[86:89], v[34:49]
	ds_read_b64_tr_b16 v[86:87], v85 offset:0x400
	ds_read_b64_tr_b16 v[88:89], v85 offset:0xc00
	v_mfma_f32_32x32x16_bf16 v[34:49], v[70:73], v[90:93], v[34:49]
	ds_read_b64_tr_b16 v[90:91], v85 offset:0x1400
	ds_read_b64_tr_b16 v[92:93], v85 offset:0x1c00
	v_mfma_f32_32x32x16_bf16 v[34:49], v[74:77], v[94:97], v[34:49]
	ds_read_b64_tr_b16 v[94:95], v85 offset:0x2400
	ds_read_b64_tr_b16 v[96:97], v85 offset:0x2c00
	v_mfma_f32_32x32x16_bf16 v[34:49], v[78:81], v[218:221], v[34:49]
	ds_read_b64_tr_b16 v[218:219], v85 offset:0x3400
	ds_read_b64_tr_b16 v[220:221], v85 offset:0x3c00
	s_waitcnt lgkmcnt(0)
	v_mfma_f32_32x32x16_bf16 v[18:33], v[66:69], v[86:89], v[18:33]
	ds_read_b64_tr_b16 v[86:87], v85 offset:0x600
	ds_read_b64_tr_b16 v[88:89], v85 offset:0xe00
	v_mfma_f32_32x32x16_bf16 v[18:33], v[70:73], v[90:93], v[18:33]
	ds_read_b64_tr_b16 v[90:91], v85 offset:0x1600
	ds_read_b64_tr_b16 v[92:93], v85 offset:0x1e00
	v_mfma_f32_32x32x16_bf16 v[18:33], v[74:77], v[94:97], v[18:33]
	ds_read_b64_tr_b16 v[94:95], v85 offset:0x2600
	ds_read_b64_tr_b16 v[96:97], v85 offset:0x2e00
	v_mfma_f32_32x32x16_bf16 v[18:33], v[78:81], v[218:221], v[18:33]
	ds_read_b64_tr_b16 v[218:219], v85 offset:0x3600
	ds_read_b64_tr_b16 v[220:221], v85 offset:0x3e00
	s_waitcnt lgkmcnt(0)
	v_mfma_f32_32x32x16_bf16 v[2:17], v[66:69], v[86:89], v[2:17]
	s_andn2_b64 vcc, exec, s[54:55]
	v_mfma_f32_32x32x16_bf16 v[2:17], v[70:73], v[90:93], v[2:17]
	v_mfma_f32_32x32x16_bf16 v[2:17], v[74:77], v[94:97], v[2:17]
	v_mfma_f32_32x32x16_bf16 v[2:17], v[78:81], v[218:221], v[2:17]
	s_cbranch_vccnz .LBB0_810
	v_mbcnt_lo_u32_b32 v66, -1, 0
	v_mbcnt_hi_u32_b32 v66, -1, v66
	s_xor_b32 s42, s71, 0x10000
	v_add_u32_e32 v67, s1, v66
	v_ashrrev_i32_e32 v68, 4, v67
	v_and_b32_e32 v70, 0xfffff0, v68
	v_lshlrev_b32_e32 v71, 1, v68
	v_lshlrev_b32_e32 v66, 3, v66
	v_and_or_b32 v70, v71, 8, v70
	v_and_b32_e32 v69, 0x78, v66
	v_lshrrev_b32_e32 v70, 1, v70
	v_bfe_u32 v66, v66, 5, 2
	v_lshrrev_b32_e32 v71, 1, v68
	v_or_b32_e32 v66, v70, v66
	v_and_b32_e32 v70, 3, v68
	v_lshlrev_b32_e32 v69, 1, v69
	v_and_or_b32 v70, v71, 4, v70
	v_and_b32_e32 v71, 48, v69
	v_lshlrev_b32_e32 v68, 8, v68
	v_and_b32_e32 v67, 0x70, v67
	s_add_i32 s42, s42, 0
	v_lshl_or_b32 v70, v70, 6, v71
	v_bitop3_b32 v67, v69, v68, v67 bitop3:0xde
	v_lshl_or_b32 v66, v66, 9, v70
	v_add_u32_e32 v67, s42, v67
	v_add_u32_e32 v66, s42, v66
	s_waitcnt vmcnt(7)
	ds_write_b128 v67, v[130:133]
	s_waitcnt vmcnt(6)
	ds_write_b128 v67, v[134:137] offset:16384
	s_waitcnt vmcnt(5)
	ds_write_b128 v66, v[138:141] offset:32768
	s_waitcnt vmcnt(4)
	ds_write_b128 v66, v[142:145] offset:49152
	s_waitcnt vmcnt(3)
	ds_write_b128 v67, v[146:149] offset:8192
	s_waitcnt vmcnt(2)
	ds_write_b128 v67, v[150:153] offset:24576
	s_waitcnt vmcnt(1)
	ds_write_b128 v66, v[154:157] offset:40960
	s_waitcnt vmcnt(0)
	ds_write_b128 v66, v[158:161] offset:57344
